# P5 stage 3: per-tile penalty selects and adds replaced by scalar branches on the wave-uniform tile class (included / diagonal / excluded); on top of scalarised conv row loads
# baseline (speedup 1.0000x reference)
.LBB0_856:
	s_lshl_b32 s0, s0, 2
	v_add_u32_e32 v142, s0, v132
	ds_read_b32 v120, v142
	v_add_u32_e32 v140, s0, v133
	v_cndmask_b32_e64 v143, 0, 1, s[56:57]
	v_cndmask_b32_e64 v141, 0, 1, s[18:19]
	s_and_b64 s[0:1], s[36:37], exec
	v_readfirstlane_b32 s0, v141
	v_readfirstlane_b32 s1, v143
	s_cselect_b32 s0, s0, s1
	s_bitcmp1_b32 s0, 0
	v_cndmask_b32_e64 v141, 0, 1, s[62:63]
	v_cndmask_b32_e64 v144, 0, 1, s[60:61]
	v_cndmask_b32_e64 v145, 0, 1, s[74:75]
	v_cndmask_b32_e64 v146, 0, 1, s[68:69]
	v_cndmask_b32_e64 v136, v125, v119, s[36:37]
	v_cndmask_b32_e64 v139, v127, v126, s[36:37]
	v_cndmask_b32_e64 v137, v129, v128, s[36:37]
	v_cndmask_b32_e64 v138, v131, v130, s[36:37]
	v_mov_b32_e32 v240, v136
	v_mov_b32_e32 v241, v139
	v_mov_b32_e32 v242, v137
	v_mov_b32_e32 v243, v138
	s_waitcnt lgkmcnt(0)
	v_mov_b32_e32 v121, v120
	s_cselect_b64 s[20:21], -1, 0
	s_bitcmp0_b32 s0, 0
	v_cndmask_b32_e64 v144, v141, v144, s[36:37]
	v_cndmask_b32_e64 v141, v145, v146, s[36:37]
	s_cbranch_scc1 .LBB0_858
	v_readfirstlane_b32 s100, v144
	s_cmp_lg_u64 s[26:27], 0
	s_cbranch_scc1 .Ls3_0_0d
	s_bitcmp1_b32 s100, 0
	s_cbranch_scc0 .Ls3_0_0x
	ds_read_b128 v[244:247], v140
	s_waitcnt lgkmcnt(0)
.Ls3_0_0c:
	v_pk_add_f32 v[244:245], v[120:121], v[244:245]
	v_pk_add_f32 v[246:247], v[120:121], v[246:247]
	v_exp_f32_e32 v244, v244
	v_exp_f32_e32 v245, v245
	v_exp_f32_e32 v246, v246
	v_exp_f32_e32 v247, v247
	v_pk_mul_f32 v[152:153], v[44:45], v[244:245]
	v_pk_mul_f32 v[154:155], v[46:47], v[246:247]
	s_branch .Ls3_0_0j
.Ls3_0_0d:
	ds_read_b128 v[244:247], v140
	s_waitcnt lgkmcnt(0)
	v_pk_add_f32 v[244:245], v[240:241], v[244:245]
	v_pk_add_f32 v[246:247], v[242:243], v[246:247]
	s_branch .Ls3_0_0c
.Ls3_0_0x:
	v_mov_b32_e32 v152, 0
	v_mov_b32_e32 v153, 0
	v_mov_b32_e32 v154, 0
	v_mov_b32_e32 v155, 0
.Ls3_0_0j:
	v_readfirstlane_b32 s100, v141
	s_cmp_lg_u64 s[4:5], 0
	s_cbranch_scc1 .Ls3_0_1d
	s_bitcmp1_b32 s100, 0
	s_cbranch_scc0 .Ls3_0_1x
	ds_read_b128 v[244:247], v140 offset:64
	s_waitcnt lgkmcnt(0)
.Ls3_0_1c:
	v_pk_add_f32 v[244:245], v[120:121], v[244:245]
	v_pk_add_f32 v[246:247], v[120:121], v[246:247]
	v_exp_f32_e32 v244, v244
	v_exp_f32_e32 v245, v245
	v_exp_f32_e32 v246, v246
	v_exp_f32_e32 v247, v247
	v_pk_mul_f32 v[156:157], v[52:53], v[244:245]
	v_pk_mul_f32 v[158:159], v[54:55], v[246:247]
	s_branch .Ls3_0_1j
.Ls3_0_1d:
	ds_read_b128 v[244:247], v140 offset:64
	s_waitcnt lgkmcnt(0)
	v_pk_add_f32 v[244:245], v[240:241], v[244:245]
	v_pk_add_f32 v[246:247], v[242:243], v[246:247]
	s_branch .Ls3_0_1c
.Ls3_0_1x:
	v_mov_b32_e32 v156, 0
	v_mov_b32_e32 v157, 0
	v_mov_b32_e32 v158, 0
	v_mov_b32_e32 v159, 0
.Ls3_0_1j:
	v_cvt_pk_bf16_f32 v148, v152, v153
	v_cvt_pk_bf16_f32 v149, v154, v155
	v_cvt_pk_bf16_f32 v150, v156, v157
	s_nop 0
	v_cvt_pk_bf16_f32 v151, v158, v159
	ds_read_b64_tr_b16 v[154:155], v134 offset:43520
	ds_read_b64_tr_b16 v[152:153], v134 offset:34816
	ds_read_b64_tr_b16 v[156:157], v134 offset:34848
	s_waitcnt lgkmcnt(1)
	v_mfma_f32_16x16x32_bf16 v[92:95], v[152:155], v[148:151], v[92:95]
	ds_read_b64_tr_b16 v[158:159], v134 offset:43552
	ds_read_b64_tr_b16 v[152:153], v134 offset:34880
	ds_read_b64_tr_b16 v[154:155], v134 offset:43584
	s_waitcnt lgkmcnt(0)
	v_mfma_f32_16x16x32_bf16 v[68:71], v[152:155], v[148:151], v[68:71]
	ds_read_b64_tr_b16 v[152:153], v134 offset:34912
	ds_read_b64_tr_b16 v[154:155], v134 offset:43616
	v_mfma_f32_16x16x32_bf16 v[80:83], v[156:159], v[148:151], v[80:83]
	s_waitcnt lgkmcnt(0)
	v_mfma_f32_16x16x32_bf16 v[60:63], v[152:155], v[148:151], v[60:63]
.LBB0_858:
	v_cndmask_b32_e64 v145, 0, 1, s[76:77]
	s_and_b64 s[0:1], s[36:37], exec
	v_readfirstlane_b32 s0, v146
	v_readfirstlane_b32 s1, v145
	s_cselect_b32 s0, s0, s1
	s_bitcmp1_b32 s0, 0
	v_cndmask_b32_e64 v146, 0, 1, s[80:81]
	v_cndmask_b32_e64 v147, 0, 1, s[88:89]
	v_cndmask_b32_e64 v148, 0, 1, s[84:85]
	s_cselect_b64 s[22:23], -1, 0
	s_bitcmp0_b32 s0, 0
	v_cndmask_b32_e64 v146, v143, v146, s[36:37]
	v_cndmask_b32_e64 v143, v147, v148, s[36:37]
	s_cbranch_scc1 .LBB0_860
	v_readfirstlane_b32 s100, v146
	s_cmp_lg_u64 s[6:7], 0
	s_cbranch_scc1 .Ls3_1_0d
	s_bitcmp1_b32 s100, 0
	s_cbranch_scc0 .Ls3_1_0x
	ds_read_b128 v[244:247], v140 offset:128
	s_waitcnt lgkmcnt(0)
.Ls3_1_0c:
	v_pk_add_f32 v[244:245], v[120:121], v[244:245]
	v_pk_add_f32 v[246:247], v[120:121], v[246:247]
	v_exp_f32_e32 v244, v244
	v_exp_f32_e32 v245, v245
	v_exp_f32_e32 v246, v246
	v_exp_f32_e32 v247, v247
	v_pk_mul_f32 v[154:155], v[56:57], v[244:245]
	v_pk_mul_f32 v[156:157], v[58:59], v[246:247]
	s_branch .Ls3_1_0j
.Ls3_1_0d:
	ds_read_b128 v[244:247], v140 offset:128
	s_waitcnt lgkmcnt(0)
	v_pk_add_f32 v[244:245], v[240:241], v[244:245]
	v_pk_add_f32 v[246:247], v[242:243], v[246:247]
	s_branch .Ls3_1_0c
.Ls3_1_0x:
	v_mov_b32_e32 v154, 0
	v_mov_b32_e32 v155, 0
	v_mov_b32_e32 v156, 0
	v_mov_b32_e32 v157, 0
.Ls3_1_0j:
	v_readfirstlane_b32 s100, v143
	s_cmp_lg_u64 s[8:9], 0
	s_cbranch_scc1 .Ls3_1_1d
	s_bitcmp1_b32 s100, 0
	s_cbranch_scc0 .Ls3_1_1x
	ds_read_b128 v[244:247], v140 offset:192
	s_waitcnt lgkmcnt(0)
.Ls3_1_1c:
	v_pk_add_f32 v[244:245], v[120:121], v[244:245]
	v_pk_add_f32 v[246:247], v[120:121], v[246:247]
	v_exp_f32_e32 v244, v244
	v_exp_f32_e32 v245, v245
	v_exp_f32_e32 v246, v246
	v_exp_f32_e32 v247, v247
	v_pk_mul_f32 v[158:159], v[64:65], v[244:245]
	v_pk_mul_f32 v[162:163], v[66:67], v[246:247]
	s_branch .Ls3_1_1j
.Ls3_1_1d:
	ds_read_b128 v[244:247], v140 offset:192
	s_waitcnt lgkmcnt(0)
	v_pk_add_f32 v[244:245], v[240:241], v[244:245]
	v_pk_add_f32 v[246:247], v[242:243], v[246:247]
	s_branch .Ls3_1_1c
.Ls3_1_1x:
	v_mov_b32_e32 v158, 0
	v_mov_b32_e32 v159, 0
	v_mov_b32_e32 v162, 0
	v_mov_b32_e32 v163, 0
.Ls3_1_1j:
	v_cvt_pk_bf16_f32 v150, v154, v155
	v_cvt_pk_bf16_f32 v151, v156, v157
	v_cvt_pk_bf16_f32 v152, v158, v159
	s_nop 0
	v_cvt_pk_bf16_f32 v153, v162, v163
	ds_read_b64_tr_b16 v[156:157], v134 offset:60928
	ds_read_b64_tr_b16 v[154:155], v134 offset:52224
	ds_read_b64_tr_b16 v[162:163], v134 offset:52256
	s_waitcnt lgkmcnt(1)
	v_mfma_f32_16x16x32_bf16 v[92:95], v[154:157], v[150:153], v[92:95]
	ds_read_b64_tr_b16 v[164:165], v134 offset:60960
	ds_read_b64_tr_b16 v[154:155], v134 offset:52288
	ds_read_b64_tr_b16 v[156:157], v134 offset:60992
	s_waitcnt lgkmcnt(0)
	v_mfma_f32_16x16x32_bf16 v[68:71], v[154:157], v[150:153], v[68:71]
	ds_read_b64_tr_b16 v[154:155], v134 offset:52320
	ds_read_b64_tr_b16 v[156:157], v134 offset:61024
	v_mfma_f32_16x16x32_bf16 v[80:83], v[162:165], v[150:153], v[80:83]
	s_waitcnt lgkmcnt(0)
	v_mfma_f32_16x16x32_bf16 v[60:63], v[154:157], v[150:153], v[60:63]
.LBB0_860:
	v_cndmask_b32_e64 v147, 0, 1, s[94:95]
	s_and_b64 s[0:1], s[36:37], exec
	v_readfirstlane_b32 s0, v148
	v_readfirstlane_b32 s1, v147
	s_cselect_b32 s0, s0, s1
	s_bitcmp1_b32 s0, 0
	v_cndmask_b32_e64 v148, 0, 1, s[96:97]
	v_cndmask_b32_e64 v150, 0, 1, s[64:65]
	v_cndmask_b32_e64 v149, 0, 1, s[92:93]
	s_cselect_b64 s[24:25], -1, 0
	s_bitcmp0_b32 s0, 0
	v_cndmask_b32_e64 v148, v145, v148, s[36:37]
	v_cndmask_b32_e64 v145, v150, v149, s[36:37]
	s_cbranch_scc1 .LBB0_862
	v_readfirstlane_b32 s100, v148
	s_cmp_lg_u64 s[10:11], 0
	s_cbranch_scc1 .Ls3_2_0d
	s_bitcmp1_b32 s100, 0
	s_cbranch_scc0 .Ls3_2_0x
	ds_read_b128 v[244:247], v140 offset:256
	s_waitcnt lgkmcnt(0)
.Ls3_2_0c:
	v_pk_add_f32 v[244:245], v[120:121], v[244:245]
	v_pk_add_f32 v[246:247], v[120:121], v[246:247]
	v_exp_f32_e32 v244, v244
	v_exp_f32_e32 v245, v245
	v_exp_f32_e32 v246, v246
	v_exp_f32_e32 v247, v247
	v_pk_mul_f32 v[154:155], v[72:73], v[244:245]
	v_pk_mul_f32 v[156:157], v[74:75], v[246:247]
	s_branch .Ls3_2_0j
.Ls3_2_0d:
	ds_read_b128 v[244:247], v140 offset:256
	s_waitcnt lgkmcnt(0)
	v_pk_add_f32 v[244:245], v[240:241], v[244:245]
	v_pk_add_f32 v[246:247], v[242:243], v[246:247]
	s_branch .Ls3_2_0c

.Ls3_2_0j:
	v_readfirstlane_b32 s100, v145
	s_cmp_lg_u64 s[12:13], 0
	s_cbranch_scc1 .Ls3_2_1d
	s_bitcmp1_b32 s100, 0
	s_cbranch_scc0 .Ls3_2_1x
	ds_read_b128 v[244:247], v140 offset:320
	s_waitcnt lgkmcnt(0)
.Ls3_2_1c:
	v_pk_add_f32 v[244:245], v[120:121], v[244:245]
	v_pk_add_f32 v[246:247], v[120:121], v[246:247]
	v_exp_f32_e32 v244, v244
	v_exp_f32_e32 v245, v245
	v_exp_f32_e32 v246, v246
	v_exp_f32_e32 v247, v247
	v_pk_mul_f32 v[158:159], v[76:77], v[244:245]
	v_pk_mul_f32 v[162:163], v[78:79], v[246:247]
	s_branch .Ls3_2_1j
.Ls3_2_1d:
	ds_read_b128 v[244:247], v140 offset:320
	s_waitcnt lgkmcnt(0)
	v_pk_add_f32 v[244:245], v[240:241], v[244:245]
	v_pk_add_f32 v[246:247], v[242:243], v[246:247]
	s_branch .Ls3_2_1c

.Ls3_2_1j:
	v_cvt_pk_bf16_f32 v150, v154, v155
	v_cvt_pk_bf16_f32 v151, v156, v157
	v_cvt_pk_bf16_f32 v152, v158, v159
	s_nop 0
	v_cvt_pk_bf16_f32 v153, v162, v163
	ds_read_b64_tr_b16 v[156:157], v135 offset:43520
	ds_read_b64_tr_b16 v[154:155], v135 offset:34816
	ds_read_b64_tr_b16 v[162:163], v135 offset:34848
	s_waitcnt lgkmcnt(1)
	v_mfma_f32_16x16x32_bf16 v[92:95], v[154:157], v[150:153], v[92:95]
	ds_read_b64_tr_b16 v[164:165], v135 offset:43552
	ds_read_b64_tr_b16 v[154:155], v135 offset:34880
	ds_read_b64_tr_b16 v[156:157], v135 offset:43584
	s_waitcnt lgkmcnt(0)
	v_mfma_f32_16x16x32_bf16 v[68:71], v[154:157], v[150:153], v[68:71]
	ds_read_b64_tr_b16 v[154:155], v135 offset:34912
	ds_read_b64_tr_b16 v[156:157], v135 offset:43616
	v_mfma_f32_16x16x32_bf16 v[80:83], v[162:165], v[150:153], v[80:83]
	s_waitcnt lgkmcnt(0)
	v_mfma_f32_16x16x32_bf16 v[60:63], v[154:157], v[150:153], v[60:63]
.LBB0_862:
	v_cndmask_b32_e64 v150, 0, 1, s[42:43]
	s_and_b64 s[0:1], s[36:37], exec
	v_readfirstlane_b32 s0, v149
	v_readfirstlane_b32 s1, v150
	s_cselect_b32 s0, s0, s1
	s_bitcmp1_b32 s0, 0
	v_cndmask_b32_e64 v149, 0, 1, s[58:59]
	v_cndmask_b32_e64 v150, 0, 1, s[90:91]
	v_cndmask_b32_e64 v151, 0, 1, s[66:67]
	s_cselect_b64 s[40:41], -1, 0
	s_bitcmp0_b32 s0, 0
	v_cndmask_b32_e64 v149, v147, v149, s[36:37]
	v_cndmask_b32_e64 v147, v150, v151, s[36:37]
	s_cbranch_scc1 .LBB0_864
	v_readfirstlane_b32 s100, v149
	s_cmp_lg_u64 s[14:15], 0
	s_cbranch_scc1 .Ls3_3_0d
	s_bitcmp1_b32 s100, 0
	s_cbranch_scc0 .Ls3_3_0x
	ds_read_b128 v[244:247], v140 offset:384
	s_waitcnt lgkmcnt(0)
.Ls3_3_0c:
	v_pk_add_f32 v[244:245], v[120:121], v[244:245]
	v_pk_add_f32 v[246:247], v[120:121], v[246:247]
	v_exp_f32_e32 v244, v244
	v_exp_f32_e32 v245, v245
	v_exp_f32_e32 v246, v246
	v_exp_f32_e32 v247, v247
	v_pk_mul_f32 v[154:155], v[84:85], v[244:245]
	v_pk_mul_f32 v[156:157], v[86:87], v[246:247]
	s_branch .Ls3_3_0j
.Ls3_3_0d:
	ds_read_b128 v[244:247], v140 offset:384
	s_waitcnt lgkmcnt(0)
	v_pk_add_f32 v[244:245], v[240:241], v[244:245]
	v_pk_add_f32 v[246:247], v[242:243], v[246:247]
	s_branch .Ls3_3_0c

.Ls3_3_0j:
	v_readfirstlane_b32 s100, v147
	s_cmp_lg_u64 s[16:17], 0
	s_cbranch_scc1 .Ls3_3_1d
	s_bitcmp1_b32 s100, 0
	s_cbranch_scc0 .Ls3_3_1x
	ds_read_b128 v[244:247], v140 offset:448
	s_waitcnt lgkmcnt(0)
.Ls3_3_1c:
	v_pk_add_f32 v[244:245], v[120:121], v[244:245]
	v_pk_add_f32 v[246:247], v[120:121], v[246:247]
	v_exp_f32_e32 v244, v244
	v_exp_f32_e32 v245, v245
	v_exp_f32_e32 v246, v246
	v_exp_f32_e32 v247, v247
	v_pk_mul_f32 v[152:153], v[88:89], v[244:245]
	v_pk_mul_f32 v[120:121], v[90:91], v[246:247]
	s_branch .Ls3_3_1j
.Ls3_3_1d:
	ds_read_b128 v[244:247], v140 offset:448
	s_waitcnt lgkmcnt(0)
	v_pk_add_f32 v[244:245], v[240:241], v[244:245]
	v_pk_add_f32 v[246:247], v[242:243], v[246:247]
	s_branch .Ls3_3_1c
.Ls3_3_1x:
	v_mov_b32_e32 v152, 0
	v_mov_b32_e32 v153, 0
	v_mov_b32_e32 v120, 0
	v_mov_b32_e32 v121, 0
.Ls3_3_1j:
	v_cvt_pk_bf16_f32 v150, v154, v155
	v_cvt_pk_bf16_f32 v151, v156, v157
	v_cvt_pk_bf16_f32 v152, v152, v153
	s_nop 0
	v_cvt_pk_bf16_f32 v153, v120, v121
	ds_read_b64_tr_b16 v[156:157], v135 offset:60928
	ds_read_b64_tr_b16 v[154:155], v135 offset:52224
	ds_read_b64_tr_b16 v[162:163], v135 offset:52256
	s_waitcnt lgkmcnt(1)
	v_mfma_f32_16x16x32_bf16 v[92:95], v[154:157], v[150:153], v[92:95]
	ds_read_b64_tr_b16 v[164:165], v135 offset:60960
	ds_read_b64_tr_b16 v[154:155], v135 offset:52288
	ds_read_b64_tr_b16 v[156:157], v135 offset:60992
	s_waitcnt lgkmcnt(0)
	v_mfma_f32_16x16x32_bf16 v[68:71], v[154:157], v[150:153], v[68:71]
	ds_read_b64_tr_b16 v[154:155], v135 offset:52320
	ds_read_b64_tr_b16 v[156:157], v135 offset:61024
	v_mfma_f32_16x16x32_bf16 v[80:83], v[162:165], v[150:153], v[80:83]
	s_waitcnt lgkmcnt(0)
	v_mfma_f32_16x16x32_bf16 v[60:63], v[154:157], v[150:153], v[60:63]
.LBB0_864:
	ds_read_b32 v120, v142 offset:512
	v_cndmask_b32_e64 v121, 0, 1, s[20:21]
	v_cmp_ne_u32_e64 s[0:1], 1, v121
	s_andn2_b64 vcc, exec, s[20:21]
	s_waitcnt lgkmcnt(0)
	v_mov_b32_e32 v121, v120
	s_cbranch_vccnz .LBB0_866
	v_readfirstlane_b32 s100, v144
	s_cmp_lg_u64 s[26:27], 0
	s_cbranch_scc1 .Ls3_4_0d
	s_bitcmp1_b32 s100, 0
	s_cbranch_scc0 .Ls3_4_0x
	ds_read_b128 v[244:247], v140 offset:512
	s_waitcnt lgkmcnt(0)
.Ls3_4_0c:
	v_pk_add_f32 v[244:245], v[120:121], v[244:245]
	v_pk_add_f32 v[246:247], v[120:121], v[246:247]
	v_exp_f32_e32 v244, v244
	v_exp_f32_e32 v245, v245
	v_exp_f32_e32 v246, v246
	v_exp_f32_e32 v247, v247
	v_pk_mul_f32 v[154:155], v[44:45], v[244:245]
	v_pk_mul_f32 v[156:157], v[46:47], v[246:247]
	s_branch .Ls3_4_0j
.Ls3_4_0d:
	ds_read_b128 v[244:247], v140 offset:512
	s_waitcnt lgkmcnt(0)
	v_pk_add_f32 v[244:245], v[240:241], v[244:245]
	v_pk_add_f32 v[246:247], v[242:243], v[246:247]
	s_branch .Ls3_4_0c

.Ls3_4_0j:
	v_readfirstlane_b32 s100, v141
	s_cmp_lg_u64 s[4:5], 0
	s_cbranch_scc1 .Ls3_4_1d
	s_bitcmp1_b32 s100, 0
	s_cbranch_scc0 .Ls3_4_1x
	ds_read_b128 v[244:247], v140 offset:576
	s_waitcnt lgkmcnt(0)
.Ls3_4_1c:
	v_pk_add_f32 v[244:245], v[120:121], v[244:245]
	v_pk_add_f32 v[246:247], v[120:121], v[246:247]
	v_exp_f32_e32 v244, v244
	v_exp_f32_e32 v245, v245
	v_exp_f32_e32 v246, v246
	v_exp_f32_e32 v247, v247
	v_pk_mul_f32 v[158:159], v[52:53], v[244:245]
	v_pk_mul_f32 v[162:163], v[54:55], v[246:247]
	s_branch .Ls3_4_1j
.Ls3_4_1d:
	ds_read_b128 v[244:247], v140 offset:576
	s_waitcnt lgkmcnt(0)
	v_pk_add_f32 v[244:245], v[240:241], v[244:245]
	v_pk_add_f32 v[246:247], v[242:243], v[246:247]
	s_branch .Ls3_4_1c

.Ls3_4_1j:
	v_cvt_pk_bf16_f32 v150, v154, v155
	v_cvt_pk_bf16_f32 v151, v156, v157
	v_cvt_pk_bf16_f32 v152, v158, v159
	s_nop 0
	v_cvt_pk_bf16_f32 v153, v162, v163
	ds_read_b64_tr_b16 v[156:157], v134 offset:43648
	ds_read_b64_tr_b16 v[154:155], v134 offset:34944
	ds_read_b64_tr_b16 v[162:163], v134 offset:34976
	s_waitcnt lgkmcnt(1)
	v_mfma_f32_16x16x32_bf16 v[48:51], v[154:157], v[150:153], v[48:51]
	ds_read_b64_tr_b16 v[164:165], v134 offset:43680
	ds_read_b64_tr_b16 v[154:155], v134 offset:35008
	ds_read_b64_tr_b16 v[156:157], v134 offset:43712
	s_waitcnt lgkmcnt(0)
	v_mfma_f32_16x16x32_bf16 v[36:39], v[154:157], v[150:153], v[36:39]
	ds_read_b64_tr_b16 v[154:155], v134 offset:35040
	ds_read_b64_tr_b16 v[156:157], v134 offset:43744
	v_mfma_f32_16x16x32_bf16 v[40:43], v[162:165], v[150:153], v[40:43]
	s_waitcnt lgkmcnt(0)
	v_mfma_f32_16x16x32_bf16 v[24:27], v[154:157], v[150:153], v[24:27]
.LBB0_866:
	v_cndmask_b32_e64 v150, 0, 1, s[22:23]
	v_cmp_ne_u32_e64 s[20:21], 1, v150
	s_andn2_b64 vcc, exec, s[22:23]
	s_cbranch_vccnz .LBB0_868
	v_readfirstlane_b32 s100, v146
	s_cmp_lg_u64 s[6:7], 0
	s_cbranch_scc1 .Ls3_5_0d
	s_bitcmp1_b32 s100, 0
	s_cbranch_scc0 .Ls3_5_0x
	ds_read_b128 v[244:247], v140 offset:640
	s_waitcnt lgkmcnt(0)

.Ls3_5_0d:
	ds_read_b128 v[244:247], v140 offset:640
	s_waitcnt lgkmcnt(0)
	v_pk_add_f32 v[244:245], v[240:241], v[244:245]
	v_pk_add_f32 v[246:247], v[242:243], v[246:247]
	s_branch .Ls3_5_0c

.Ls3_5_0j:
	v_readfirstlane_b32 s100, v143
	s_cmp_lg_u64 s[8:9], 0
	s_cbranch_scc1 .Ls3_5_1d
	s_bitcmp1_b32 s100, 0
	s_cbranch_scc0 .Ls3_5_1x
	ds_read_b128 v[244:247], v140 offset:704
	s_waitcnt lgkmcnt(0)

.Ls3_5_1d:
	ds_read_b128 v[244:247], v140 offset:704
	s_waitcnt lgkmcnt(0)
	v_pk_add_f32 v[244:245], v[240:241], v[244:245]
	v_pk_add_f32 v[246:247], v[242:243], v[246:247]
	s_branch .Ls3_5_1c

.Ls3_5_1j:
	v_cvt_pk_bf16_f32 v150, v154, v155
	v_cvt_pk_bf16_f32 v151, v156, v157
	v_cvt_pk_bf16_f32 v152, v158, v159
	s_nop 0
	v_cvt_pk_bf16_f32 v153, v162, v163
	ds_read_b64_tr_b16 v[156:157], v134 offset:61056
	ds_read_b64_tr_b16 v[154:155], v134 offset:52352
	ds_read_b64_tr_b16 v[162:163], v134 offset:52384
	s_waitcnt lgkmcnt(1)
	v_mfma_f32_16x16x32_bf16 v[48:51], v[154:157], v[150:153], v[48:51]
	ds_read_b64_tr_b16 v[164:165], v134 offset:61088
	ds_read_b64_tr_b16 v[154:155], v134 offset:52416
	ds_read_b64_tr_b16 v[156:157], v134 offset:61120
	s_waitcnt lgkmcnt(0)
	v_mfma_f32_16x16x32_bf16 v[36:39], v[154:157], v[150:153], v[36:39]
	ds_read_b64_tr_b16 v[154:155], v134 offset:52448
	ds_read_b64_tr_b16 v[156:157], v134 offset:61152
	v_mfma_f32_16x16x32_bf16 v[40:43], v[162:165], v[150:153], v[40:43]
	s_waitcnt lgkmcnt(0)
	v_mfma_f32_16x16x32_bf16 v[24:27], v[154:157], v[150:153], v[24:27]
.LBB0_868:
	v_cndmask_b32_e64 v150, 0, 1, s[24:25]
	v_cmp_ne_u32_e64 s[22:23], 1, v150
	s_andn2_b64 vcc, exec, s[24:25]
	s_cbranch_vccnz .LBB0_870
	v_readfirstlane_b32 s100, v148
	s_cmp_lg_u64 s[10:11], 0
	s_cbranch_scc1 .Ls3_6_0d
	s_bitcmp1_b32 s100, 0
	s_cbranch_scc0 .Ls3_6_0x
	ds_read_b128 v[244:247], v140 offset:768
	s_waitcnt lgkmcnt(0)

.Ls3_6_0d:
	ds_read_b128 v[244:247], v140 offset:768
	s_waitcnt lgkmcnt(0)
	v_pk_add_f32 v[244:245], v[240:241], v[244:245]
	v_pk_add_f32 v[246:247], v[242:243], v[246:247]
	s_branch .Ls3_6_0c

.Ls3_6_0j:
	v_readfirstlane_b32 s100, v145
	s_cmp_lg_u64 s[12:13], 0
	s_cbranch_scc1 .Ls3_6_1d
	s_bitcmp1_b32 s100, 0
	s_cbranch_scc0 .Ls3_6_1x
	ds_read_b128 v[244:247], v140 offset:832
	s_waitcnt lgkmcnt(0)

.Ls3_6_1d:
	ds_read_b128 v[244:247], v140 offset:832
	s_waitcnt lgkmcnt(0)
	v_pk_add_f32 v[244:245], v[240:241], v[244:245]
	v_pk_add_f32 v[246:247], v[242:243], v[246:247]
	s_branch .Ls3_6_1c

.Ls3_6_1j:
	v_cvt_pk_bf16_f32 v150, v154, v155
	v_cvt_pk_bf16_f32 v151, v156, v157
	v_cvt_pk_bf16_f32 v152, v158, v159
	s_nop 0
	v_cvt_pk_bf16_f32 v153, v162, v163
	ds_read_b64_tr_b16 v[156:157], v135 offset:43648
	ds_read_b64_tr_b16 v[154:155], v135 offset:34944
	ds_read_b64_tr_b16 v[162:163], v135 offset:34976
	s_waitcnt lgkmcnt(1)
	v_mfma_f32_16x16x32_bf16 v[48:51], v[154:157], v[150:153], v[48:51]
	ds_read_b64_tr_b16 v[164:165], v135 offset:43680
	ds_read_b64_tr_b16 v[154:155], v135 offset:35008
	ds_read_b64_tr_b16 v[156:157], v135 offset:43712
	s_waitcnt lgkmcnt(0)
	v_mfma_f32_16x16x32_bf16 v[36:39], v[154:157], v[150:153], v[36:39]
	ds_read_b64_tr_b16 v[154:155], v135 offset:35040
	ds_read_b64_tr_b16 v[156:157], v135 offset:43744
	v_mfma_f32_16x16x32_bf16 v[40:43], v[162:165], v[150:153], v[40:43]
	s_waitcnt lgkmcnt(0)
	v_mfma_f32_16x16x32_bf16 v[24:27], v[154:157], v[150:153], v[24:27]
.LBB0_870:
	v_cndmask_b32_e64 v150, 0, 1, s[40:41]
	v_cmp_ne_u32_e64 s[24:25], 1, v150
	s_andn2_b64 vcc, exec, s[40:41]
	s_cbranch_vccnz .LBB0_872
	v_readfirstlane_b32 s100, v149
	s_cmp_lg_u64 s[14:15], 0
	s_cbranch_scc1 .Ls3_7_0d
	s_bitcmp1_b32 s100, 0
	s_cbranch_scc0 .Ls3_7_0x
	ds_read_b128 v[244:247], v140 offset:896
	s_waitcnt lgkmcnt(0)

.Ls3_7_0d:
	ds_read_b128 v[244:247], v140 offset:896
	s_waitcnt lgkmcnt(0)
	v_pk_add_f32 v[244:245], v[240:241], v[244:245]
	v_pk_add_f32 v[246:247], v[242:243], v[246:247]
	s_branch .Ls3_7_0c

.Ls3_7_0j:
	v_readfirstlane_b32 s100, v147
	s_cmp_lg_u64 s[16:17], 0
	s_cbranch_scc1 .Ls3_7_1d
	s_bitcmp1_b32 s100, 0
	s_cbranch_scc0 .Ls3_7_1x
	ds_read_b128 v[244:247], v140 offset:960
	s_waitcnt lgkmcnt(0)

.Ls3_7_1d:
	ds_read_b128 v[244:247], v140 offset:960
	s_waitcnt lgkmcnt(0)
	v_pk_add_f32 v[244:245], v[240:241], v[244:245]
	v_pk_add_f32 v[246:247], v[242:243], v[246:247]
	s_branch .Ls3_7_1c

.Ls3_7_1j:
	v_cvt_pk_bf16_f32 v150, v154, v155
	v_cvt_pk_bf16_f32 v151, v156, v157
	v_cvt_pk_bf16_f32 v152, v152, v153
	s_nop 0
	v_cvt_pk_bf16_f32 v153, v120, v121
	ds_read_b64_tr_b16 v[156:157], v135 offset:61056
	ds_read_b64_tr_b16 v[154:155], v135 offset:52352
	ds_read_b64_tr_b16 v[162:163], v135 offset:52384
	s_waitcnt lgkmcnt(1)
	v_mfma_f32_16x16x32_bf16 v[48:51], v[154:157], v[150:153], v[48:51]
	ds_read_b64_tr_b16 v[164:165], v135 offset:61088
	ds_read_b64_tr_b16 v[154:155], v135 offset:52416
	ds_read_b64_tr_b16 v[156:157], v135 offset:61120
	s_waitcnt lgkmcnt(0)
	v_mfma_f32_16x16x32_bf16 v[36:39], v[154:157], v[150:153], v[36:39]
	ds_read_b64_tr_b16 v[154:155], v135 offset:52448
	ds_read_b64_tr_b16 v[156:157], v135 offset:61152
	v_mfma_f32_16x16x32_bf16 v[40:43], v[162:165], v[150:153], v[40:43]
	s_waitcnt lgkmcnt(0)
	v_mfma_f32_16x16x32_bf16 v[24:27], v[154:157], v[150:153], v[24:27]
.LBB0_872:
	ds_read_b32 v120, v142 offset:1024
	s_and_b64 vcc, exec, s[0:1]
	s_waitcnt lgkmcnt(0)
	v_mov_b32_e32 v121, v120
	s_cbranch_vccnz .LBB0_874
	v_readfirstlane_b32 s100, v144
	s_cmp_lg_u64 s[26:27], 0
	s_cbranch_scc1 .Ls3_8_0d
	s_bitcmp1_b32 s100, 0
	s_cbranch_scc0 .Ls3_8_0x
	ds_read_b128 v[244:247], v140 offset:1024
	s_waitcnt lgkmcnt(0)

.Ls3_8_0d:
	ds_read_b128 v[244:247], v140 offset:1024
	s_waitcnt lgkmcnt(0)
	v_pk_add_f32 v[244:245], v[240:241], v[244:245]
	v_pk_add_f32 v[246:247], v[242:243], v[246:247]
	s_branch .Ls3_8_0c

.Ls3_8_0j:
	v_readfirstlane_b32 s100, v141
	s_cmp_lg_u64 s[4:5], 0
	s_cbranch_scc1 .Ls3_8_1d
	s_bitcmp1_b32 s100, 0
	s_cbranch_scc0 .Ls3_8_1x
	ds_read_b128 v[244:247], v140 offset:1088
	s_waitcnt lgkmcnt(0)

.Ls3_8_1d:
	ds_read_b128 v[244:247], v140 offset:1088
	s_waitcnt lgkmcnt(0)
	v_pk_add_f32 v[244:245], v[240:241], v[244:245]
	v_pk_add_f32 v[246:247], v[242:243], v[246:247]
	s_branch .Ls3_8_1c

.Ls3_8_1j:
	v_cvt_pk_bf16_f32 v150, v154, v155
	v_cvt_pk_bf16_f32 v151, v156, v157
	v_cvt_pk_bf16_f32 v152, v158, v159
	s_nop 0
	v_cvt_pk_bf16_f32 v153, v162, v163
	ds_read_b64_tr_b16 v[156:157], v134 offset:43776
	ds_read_b64_tr_b16 v[154:155], v134 offset:35072
	ds_read_b64_tr_b16 v[162:163], v134 offset:35104
	s_waitcnt lgkmcnt(1)
	v_mfma_f32_16x16x32_bf16 v[32:35], v[154:157], v[150:153], v[32:35]
	ds_read_b64_tr_b16 v[164:165], v134 offset:43808
	ds_read_b64_tr_b16 v[154:155], v134 offset:35136
	ds_read_b64_tr_b16 v[156:157], v134 offset:43840
	s_waitcnt lgkmcnt(0)
	v_mfma_f32_16x16x32_bf16 v[20:23], v[154:157], v[150:153], v[20:23]
	ds_read_b64_tr_b16 v[154:155], v134 offset:35168
	ds_read_b64_tr_b16 v[156:157], v134 offset:43872
	v_mfma_f32_16x16x32_bf16 v[28:31], v[162:165], v[150:153], v[28:31]
	s_waitcnt lgkmcnt(0)
	v_mfma_f32_16x16x32_bf16 v[16:19], v[154:157], v[150:153], v[16:19]
.LBB0_874:
	s_and_b64 vcc, exec, s[20:21]
	s_cbranch_vccnz .LBB0_876
	v_readfirstlane_b32 s100, v146
	s_cmp_lg_u64 s[6:7], 0
	s_cbranch_scc1 .Ls3_9_0d
	s_bitcmp1_b32 s100, 0
	s_cbranch_scc0 .Ls3_9_0x
	ds_read_b128 v[244:247], v140 offset:1152
	s_waitcnt lgkmcnt(0)

.Ls3_9_0d:
	ds_read_b128 v[244:247], v140 offset:1152
	s_waitcnt lgkmcnt(0)
	v_pk_add_f32 v[244:245], v[240:241], v[244:245]
	v_pk_add_f32 v[246:247], v[242:243], v[246:247]
	s_branch .Ls3_9_0c

.Ls3_9_0j:
	v_readfirstlane_b32 s100, v143
	s_cmp_lg_u64 s[8:9], 0
	s_cbranch_scc1 .Ls3_9_1d
	s_bitcmp1_b32 s100, 0
	s_cbranch_scc0 .Ls3_9_1x
	ds_read_b128 v[244:247], v140 offset:1216
	s_waitcnt lgkmcnt(0)

.Ls3_9_1d:
	ds_read_b128 v[244:247], v140 offset:1216
	s_waitcnt lgkmcnt(0)
	v_pk_add_f32 v[244:245], v[240:241], v[244:245]
	v_pk_add_f32 v[246:247], v[242:243], v[246:247]
	s_branch .Ls3_9_1c

.Ls3_9_1j:
	v_cvt_pk_bf16_f32 v150, v154, v155
	v_cvt_pk_bf16_f32 v151, v156, v157
	v_cvt_pk_bf16_f32 v152, v158, v159
	s_nop 0
	v_cvt_pk_bf16_f32 v153, v162, v163
	ds_read_b64_tr_b16 v[156:157], v134 offset:61184
	ds_read_b64_tr_b16 v[154:155], v134 offset:52480
	ds_read_b64_tr_b16 v[162:163], v134 offset:52512
	s_waitcnt lgkmcnt(1)
	v_mfma_f32_16x16x32_bf16 v[32:35], v[154:157], v[150:153], v[32:35]
	ds_read_b64_tr_b16 v[164:165], v134 offset:61216
	ds_read_b64_tr_b16 v[154:155], v134 offset:52544
	ds_read_b64_tr_b16 v[156:157], v134 offset:61248
	s_waitcnt lgkmcnt(0)
	v_mfma_f32_16x16x32_bf16 v[20:23], v[154:157], v[150:153], v[20:23]
	ds_read_b64_tr_b16 v[154:155], v134 offset:52576
	ds_read_b64_tr_b16 v[156:157], v134 offset:61280
	v_mfma_f32_16x16x32_bf16 v[28:31], v[162:165], v[150:153], v[28:31]
	s_waitcnt lgkmcnt(0)
	v_mfma_f32_16x16x32_bf16 v[16:19], v[154:157], v[150:153], v[16:19]
.LBB0_876:
	s_and_b64 vcc, exec, s[22:23]
	s_cbranch_vccnz .LBB0_878
	v_readfirstlane_b32 s100, v148
	s_cmp_lg_u64 s[10:11], 0
	s_cbranch_scc1 .Ls3_10_0d
	s_bitcmp1_b32 s100, 0
	s_cbranch_scc0 .Ls3_10_0x
	ds_read_b128 v[244:247], v140 offset:1280
	s_waitcnt lgkmcnt(0)

.Ls3_10_0d:
	ds_read_b128 v[244:247], v140 offset:1280
	s_waitcnt lgkmcnt(0)
	v_pk_add_f32 v[244:245], v[240:241], v[244:245]
	v_pk_add_f32 v[246:247], v[242:243], v[246:247]
	s_branch .Ls3_10_0c

.Ls3_10_0j:
	v_readfirstlane_b32 s100, v145
	s_cmp_lg_u64 s[12:13], 0
	s_cbranch_scc1 .Ls3_10_1d
	s_bitcmp1_b32 s100, 0
	s_cbranch_scc0 .Ls3_10_1x
	ds_read_b128 v[244:247], v140 offset:1344
	s_waitcnt lgkmcnt(0)

.Ls3_10_1d:
	ds_read_b128 v[244:247], v140 offset:1344
	s_waitcnt lgkmcnt(0)
	v_pk_add_f32 v[244:245], v[240:241], v[244:245]
	v_pk_add_f32 v[246:247], v[242:243], v[246:247]
	s_branch .Ls3_10_1c

.Ls3_10_1j:
	v_cvt_pk_bf16_f32 v150, v154, v155
	v_cvt_pk_bf16_f32 v151, v156, v157
	v_cvt_pk_bf16_f32 v152, v158, v159
	s_nop 0
	v_cvt_pk_bf16_f32 v153, v162, v163
	ds_read_b64_tr_b16 v[156:157], v135 offset:43776
	ds_read_b64_tr_b16 v[154:155], v135 offset:35072
	ds_read_b64_tr_b16 v[162:163], v135 offset:35104
	s_waitcnt lgkmcnt(1)
	v_mfma_f32_16x16x32_bf16 v[32:35], v[154:157], v[150:153], v[32:35]
	ds_read_b64_tr_b16 v[164:165], v135 offset:43808
	ds_read_b64_tr_b16 v[154:155], v135 offset:35136
	ds_read_b64_tr_b16 v[156:157], v135 offset:43840
	s_waitcnt lgkmcnt(0)
	v_mfma_f32_16x16x32_bf16 v[20:23], v[154:157], v[150:153], v[20:23]
	ds_read_b64_tr_b16 v[154:155], v135 offset:35168
	ds_read_b64_tr_b16 v[156:157], v135 offset:43872
	v_mfma_f32_16x16x32_bf16 v[28:31], v[162:165], v[150:153], v[28:31]
	s_waitcnt lgkmcnt(0)
	v_mfma_f32_16x16x32_bf16 v[16:19], v[154:157], v[150:153], v[16:19]
.LBB0_878:
	s_and_b64 vcc, exec, s[24:25]
	s_cbranch_vccnz .LBB0_880
	v_readfirstlane_b32 s100, v149
	s_cmp_lg_u64 s[14:15], 0
	s_cbranch_scc1 .Ls3_11_0d
	s_bitcmp1_b32 s100, 0
	s_cbranch_scc0 .Ls3_11_0x
	ds_read_b128 v[244:247], v140 offset:1408
	s_waitcnt lgkmcnt(0)

.Ls3_11_0d:
	ds_read_b128 v[244:247], v140 offset:1408
	s_waitcnt lgkmcnt(0)
	v_pk_add_f32 v[244:245], v[240:241], v[244:245]
	v_pk_add_f32 v[246:247], v[242:243], v[246:247]
	s_branch .Ls3_11_0c

.Ls3_11_0j:
	v_readfirstlane_b32 s100, v147
	s_cmp_lg_u64 s[16:17], 0
	s_cbranch_scc1 .Ls3_11_1d
	s_bitcmp1_b32 s100, 0
	s_cbranch_scc0 .Ls3_11_1x
	ds_read_b128 v[244:247], v140 offset:1472
	s_waitcnt lgkmcnt(0)

.Ls3_11_1d:
	ds_read_b128 v[244:247], v140 offset:1472
	s_waitcnt lgkmcnt(0)
	v_pk_add_f32 v[244:245], v[240:241], v[244:245]
	v_pk_add_f32 v[246:247], v[242:243], v[246:247]
	s_branch .Ls3_11_1c

.Ls3_11_1j:
	v_cvt_pk_bf16_f32 v150, v154, v155
	v_cvt_pk_bf16_f32 v151, v156, v157
	v_cvt_pk_bf16_f32 v152, v152, v153
	s_nop 0
	v_cvt_pk_bf16_f32 v153, v120, v121
	ds_read_b64_tr_b16 v[156:157], v135 offset:61184
	ds_read_b64_tr_b16 v[154:155], v135 offset:52480
	ds_read_b64_tr_b16 v[162:163], v135 offset:52512
	s_waitcnt lgkmcnt(1)
	v_mfma_f32_16x16x32_bf16 v[32:35], v[154:157], v[150:153], v[32:35]
	ds_read_b64_tr_b16 v[164:165], v135 offset:61216
	ds_read_b64_tr_b16 v[154:155], v135 offset:52544
	ds_read_b64_tr_b16 v[156:157], v135 offset:61248
	s_waitcnt lgkmcnt(0)
	v_mfma_f32_16x16x32_bf16 v[20:23], v[154:157], v[150:153], v[20:23]
	ds_read_b64_tr_b16 v[154:155], v135 offset:52576
	ds_read_b64_tr_b16 v[156:157], v135 offset:61280
	v_mfma_f32_16x16x32_bf16 v[28:31], v[162:165], v[150:153], v[28:31]
	s_waitcnt lgkmcnt(0)
	v_mfma_f32_16x16x32_bf16 v[16:19], v[154:157], v[150:153], v[16:19]
.LBB0_880:
	ds_read_b32 v120, v142 offset:1536
	s_and_b64 vcc, exec, s[0:1]
	s_waitcnt lgkmcnt(0)
	v_mov_b32_e32 v121, v120
	s_cbranch_vccnz .LBB0_882
	v_readfirstlane_b32 s100, v144
	s_cmp_lg_u64 s[26:27], 0
	s_cbranch_scc1 .Ls3_12_0d
	s_bitcmp1_b32 s100, 0
	s_cbranch_scc0 .Ls3_12_0x
	ds_read_b128 v[244:247], v140 offset:1536
	s_waitcnt lgkmcnt(0)

.Ls3_12_0d:
	ds_read_b128 v[244:247], v140 offset:1536
	s_waitcnt lgkmcnt(0)
	v_pk_add_f32 v[244:245], v[240:241], v[244:245]
	v_pk_add_f32 v[246:247], v[242:243], v[246:247]
	s_branch .Ls3_12_0c

.Ls3_12_0j:
	v_readfirstlane_b32 s100, v141
	s_cmp_lg_u64 s[4:5], 0
	s_cbranch_scc1 .Ls3_12_1d
	s_bitcmp1_b32 s100, 0
	s_cbranch_scc0 .Ls3_12_1x
	ds_read_b128 v[244:247], v140 offset:1600
	s_waitcnt lgkmcnt(0)

.Ls3_12_1d:
	ds_read_b128 v[244:247], v140 offset:1600
	s_waitcnt lgkmcnt(0)
	v_pk_add_f32 v[244:245], v[240:241], v[244:245]
	v_pk_add_f32 v[246:247], v[242:243], v[246:247]
	s_branch .Ls3_12_1c

.Ls3_12_1j:
	v_cvt_pk_bf16_f32 v150, v154, v155
	v_cvt_pk_bf16_f32 v151, v156, v157
	v_cvt_pk_bf16_f32 v152, v158, v159
	s_nop 0
	v_cvt_pk_bf16_f32 v153, v162, v163
	ds_read_b64_tr_b16 v[156:157], v134 offset:43904
	ds_read_b64_tr_b16 v[154:155], v134 offset:35200
	ds_read_b64_tr_b16 v[162:163], v134 offset:35232
	s_waitcnt lgkmcnt(1)
	v_mfma_f32_16x16x32_bf16 v[12:15], v[154:157], v[150:153], v[12:15]
	ds_read_b64_tr_b16 v[164:165], v134 offset:43936
	ds_read_b64_tr_b16 v[154:155], v134 offset:35264
	ds_read_b64_tr_b16 v[156:157], v134 offset:43968
	s_waitcnt lgkmcnt(0)
	v_mfma_f32_16x16x32_bf16 v[4:7], v[154:157], v[150:153], v[4:7]
	ds_read_b64_tr_b16 v[154:155], v134 offset:35296
	ds_read_b64_tr_b16 v[156:157], v134 offset:44000
	v_mfma_f32_16x16x32_bf16 v[8:11], v[162:165], v[150:153], v[8:11]
	s_waitcnt lgkmcnt(0)
	v_mfma_f32_16x16x32_bf16 v[0:3], v[154:157], v[150:153], v[0:3]
.LBB0_882:
	s_and_b64 vcc, exec, s[20:21]
	s_cbranch_vccnz .LBB0_884
	v_readfirstlane_b32 s100, v146
	s_cmp_lg_u64 s[6:7], 0
	s_cbranch_scc1 .Ls3_13_0d
	s_bitcmp1_b32 s100, 0
	s_cbranch_scc0 .Ls3_13_0x
	ds_read_b128 v[244:247], v140 offset:1664
	s_waitcnt lgkmcnt(0)

.Ls3_13_0d:
	ds_read_b128 v[244:247], v140 offset:1664
	s_waitcnt lgkmcnt(0)
	v_pk_add_f32 v[244:245], v[240:241], v[244:245]
	v_pk_add_f32 v[246:247], v[242:243], v[246:247]
	s_branch .Ls3_13_0c

.Ls3_13_0j:
	v_readfirstlane_b32 s100, v143
	s_cmp_lg_u64 s[8:9], 0
	s_cbranch_scc1 .Ls3_13_1d
	s_bitcmp1_b32 s100, 0
	s_cbranch_scc0 .Ls3_13_1x
	ds_read_b128 v[244:247], v140 offset:1728
	s_waitcnt lgkmcnt(0)
.Ls3_13_1c:
	v_pk_add_f32 v[244:245], v[120:121], v[244:245]
	v_pk_add_f32 v[246:247], v[120:121], v[246:247]
	v_exp_f32_e32 v244, v244
	v_exp_f32_e32 v245, v245
	v_exp_f32_e32 v246, v246
	v_exp_f32_e32 v247, v247
	v_pk_mul_f32 v[142:143], v[64:65], v[244:245]
	v_pk_mul_f32 v[158:159], v[66:67], v[246:247]
	s_branch .Ls3_13_1j
.Ls3_13_1d:
	ds_read_b128 v[244:247], v140 offset:1728
	s_waitcnt lgkmcnt(0)
	v_pk_add_f32 v[244:245], v[240:241], v[244:245]
	v_pk_add_f32 v[246:247], v[242:243], v[246:247]
	s_branch .Ls3_13_1c
.Ls3_13_1x:
	v_mov_b32_e32 v142, 0
	v_mov_b32_e32 v143, 0
	v_mov_b32_e32 v158, 0
	v_mov_b32_e32 v159, 0
.Ls3_13_1j:
	v_cvt_pk_bf16_f32 v150, v154, v155
	v_cvt_pk_bf16_f32 v151, v156, v157
	v_cvt_pk_bf16_f32 v152, v142, v143
	s_nop 0
	v_cvt_pk_bf16_f32 v153, v158, v159
	ds_read_b64_tr_b16 v[156:157], v134 offset:61312
	ds_read_b64_tr_b16 v[154:155], v134 offset:52608
	ds_read_b64_tr_b16 v[162:163], v134 offset:52640
	s_waitcnt lgkmcnt(1)
	v_mfma_f32_16x16x32_bf16 v[12:15], v[154:157], v[150:153], v[12:15]
	ds_read_b64_tr_b16 v[164:165], v134 offset:61344
	ds_read_b64_tr_b16 v[154:155], v134 offset:52672
	ds_read_b64_tr_b16 v[156:157], v134 offset:61376
	s_waitcnt lgkmcnt(0)
	v_mfma_f32_16x16x32_bf16 v[4:7], v[154:157], v[150:153], v[4:7]
	ds_read_b64_tr_b16 v[154:155], v134 offset:52704
	ds_read_b64_tr_b16 v[156:157], v134 offset:61408
	v_mfma_f32_16x16x32_bf16 v[8:11], v[162:165], v[150:153], v[8:11]
	s_waitcnt lgkmcnt(0)
	v_mfma_f32_16x16x32_bf16 v[0:3], v[154:157], v[150:153], v[0:3]
.LBB0_884:
	s_and_b64 vcc, exec, s[22:23]
	s_cbranch_vccnz .LBB0_886
	v_readfirstlane_b32 s100, v148
	s_cmp_lg_u64 s[10:11], 0
	s_cbranch_scc1 .Ls3_14_0d
	s_bitcmp1_b32 s100, 0
	s_cbranch_scc0 .Ls3_14_0x
	ds_read_b128 v[244:247], v140 offset:1792
	s_waitcnt lgkmcnt(0)
.Ls3_14_0c:
	v_pk_add_f32 v[244:245], v[120:121], v[244:245]
	v_pk_add_f32 v[246:247], v[120:121], v[246:247]
	v_exp_f32_e32 v244, v244
	v_exp_f32_e32 v245, v245
	v_exp_f32_e32 v246, v246
	v_exp_f32_e32 v247, v247
	v_pk_mul_f32 v[152:153], v[72:73], v[244:245]
	v_pk_mul_f32 v[150:151], v[74:75], v[246:247]
	s_branch .Ls3_14_0j
.Ls3_14_0d:
	ds_read_b128 v[244:247], v140 offset:1792
	s_waitcnt lgkmcnt(0)
	v_pk_add_f32 v[244:245], v[240:241], v[244:245]
	v_pk_add_f32 v[246:247], v[242:243], v[246:247]
	s_branch .Ls3_14_0c
.Ls3_14_0x:
	v_mov_b32_e32 v152, 0
	v_mov_b32_e32 v153, 0
	v_mov_b32_e32 v150, 0
	v_mov_b32_e32 v151, 0
.Ls3_14_0j:
	v_readfirstlane_b32 s100, v145
	s_cmp_lg_u64 s[12:13], 0
	s_cbranch_scc1 .Ls3_14_1d
	s_bitcmp1_b32 s100, 0
	s_cbranch_scc0 .Ls3_14_1x
	ds_read_b128 v[244:247], v140 offset:1856
	s_waitcnt lgkmcnt(0)
.Ls3_14_1c:
	v_pk_add_f32 v[244:245], v[120:121], v[244:245]
	v_pk_add_f32 v[246:247], v[120:121], v[246:247]
	v_exp_f32_e32 v244, v244
	v_exp_f32_e32 v245, v245
	v_exp_f32_e32 v246, v246
	v_exp_f32_e32 v247, v247
	v_pk_mul_f32 v[154:155], v[76:77], v[244:245]
	v_pk_mul_f32 v[156:157], v[78:79], v[246:247]
	s_branch .Ls3_14_1j
.Ls3_14_1d:
	ds_read_b128 v[244:247], v140 offset:1856
	s_waitcnt lgkmcnt(0)
	v_pk_add_f32 v[244:245], v[240:241], v[244:245]
	v_pk_add_f32 v[246:247], v[242:243], v[246:247]
	s_branch .Ls3_14_1c

.Ls3_14_1j:
	v_cvt_pk_bf16_f32 v142, v152, v153
	v_cvt_pk_bf16_f32 v143, v150, v151
	v_cvt_pk_bf16_f32 v144, v154, v155
	s_nop 0
	v_cvt_pk_bf16_f32 v145, v156, v157
	ds_read_b64_tr_b16 v[152:153], v135 offset:43904
	ds_read_b64_tr_b16 v[150:151], v135 offset:35200
	ds_read_b64_tr_b16 v[154:155], v135 offset:35232
	s_waitcnt lgkmcnt(1)
	v_mfma_f32_16x16x32_bf16 v[12:15], v[150:153], v[142:145], v[12:15]
	ds_read_b64_tr_b16 v[156:157], v135 offset:43936
	ds_read_b64_tr_b16 v[150:151], v135 offset:35264
	ds_read_b64_tr_b16 v[152:153], v135 offset:43968
	s_waitcnt lgkmcnt(0)
	v_mfma_f32_16x16x32_bf16 v[4:7], v[150:153], v[142:145], v[4:7]
	ds_read_b64_tr_b16 v[150:151], v135 offset:35296
	ds_read_b64_tr_b16 v[152:153], v135 offset:44000
	v_mfma_f32_16x16x32_bf16 v[8:11], v[154:157], v[142:145], v[8:11]
	s_waitcnt lgkmcnt(0)
	v_mfma_f32_16x16x32_bf16 v[0:3], v[150:153], v[142:145], v[0:3]
.LBB0_886:
	s_and_b64 vcc, exec, s[24:25]
	s_cbranch_vccnz .LBB0_855
	v_readfirstlane_b32 s100, v149
	s_cmp_lg_u64 s[14:15], 0
	s_cbranch_scc1 .Ls3_15_0d
	s_bitcmp1_b32 s100, 0
	s_cbranch_scc0 .Ls3_15_0x
	ds_read_b128 v[244:247], v140 offset:1920
	s_waitcnt lgkmcnt(0)
.Ls3_15_0c:
	v_pk_add_f32 v[244:245], v[120:121], v[244:245]
	v_pk_add_f32 v[246:247], v[120:121], v[246:247]
	v_exp_f32_e32 v244, v244
	v_exp_f32_e32 v245, v245
	v_exp_f32_e32 v246, v246
	v_exp_f32_e32 v247, v247
	v_pk_mul_f32 v[148:149], v[84:85], v[244:245]
	v_pk_mul_f32 v[144:145], v[86:87], v[246:247]
	s_branch .Ls3_15_0j
.Ls3_15_0d:
	ds_read_b128 v[244:247], v140 offset:1920
	s_waitcnt lgkmcnt(0)
	v_pk_add_f32 v[244:245], v[240:241], v[244:245]
	v_pk_add_f32 v[246:247], v[242:243], v[246:247]
	s_branch .Ls3_15_0c
.Ls3_15_0x:
	v_mov_b32_e32 v148, 0
	v_mov_b32_e32 v149, 0
	v_mov_b32_e32 v144, 0
	v_mov_b32_e32 v145, 0
.Ls3_15_0j:
	v_readfirstlane_b32 s100, v147
	s_cmp_lg_u64 s[16:17], 0
	s_cbranch_scc1 .Ls3_15_1d
	s_bitcmp1_b32 s100, 0
	s_cbranch_scc0 .Ls3_15_1x
	ds_read_b128 v[244:247], v140 offset:1984
	s_waitcnt lgkmcnt(0)
.Ls3_15_1c:
	v_pk_add_f32 v[244:245], v[120:121], v[244:245]
	v_pk_add_f32 v[246:247], v[120:121], v[246:247]
	v_exp_f32_e32 v244, v244
	v_exp_f32_e32 v245, v245
	v_exp_f32_e32 v246, v246
	v_exp_f32_e32 v247, v247
	v_pk_mul_f32 v[138:139], v[88:89], v[244:245]
	v_pk_mul_f32 v[120:121], v[90:91], v[246:247]
	s_branch .Ls3_15_1j
.Ls3_15_1d:
	ds_read_b128 v[244:247], v140 offset:1984
	s_waitcnt lgkmcnt(0)
	v_pk_add_f32 v[244:245], v[240:241], v[244:245]
	v_pk_add_f32 v[246:247], v[242:243], v[246:247]
	s_branch .Ls3_15_1c
.Ls3_15_1x:
	v_mov_b32_e32 v138, 0
	v_mov_b32_e32 v139, 0
	v_mov_b32_e32 v120, 0
	v_mov_b32_e32 v121, 0
.Ls3_15_1j:
	v_cvt_pk_bf16_f32 v136, v148, v149
	v_cvt_pk_bf16_f32 v137, v144, v145
	v_cvt_pk_bf16_f32 v138, v138, v139
	s_nop 0
	v_cvt_pk_bf16_f32 v139, v120, v121
	ds_read_b64_tr_b16 v[142:143], v135 offset:61312
	ds_read_b64_tr_b16 v[140:141], v135 offset:52608
	ds_read_b64_tr_b16 v[144:145], v135 offset:52640
	s_waitcnt lgkmcnt(1)
	v_mfma_f32_16x16x32_bf16 v[12:15], v[140:143], v[136:139], v[12:15]
	ds_read_b64_tr_b16 v[146:147], v135 offset:61344
	ds_read_b64_tr_b16 v[140:141], v135 offset:52672
	ds_read_b64_tr_b16 v[142:143], v135 offset:61376
	s_waitcnt lgkmcnt(0)
	v_mfma_f32_16x16x32_bf16 v[4:7], v[140:143], v[136:139], v[4:7]
	ds_read_b64_tr_b16 v[140:141], v135 offset:52704
	ds_read_b64_tr_b16 v[142:143], v135 offset:61408
	v_mfma_f32_16x16x32_bf16 v[8:11], v[144:147], v[136:139], v[8:11]
	s_waitcnt lgkmcnt(0)
	v_mfma_f32_16x16x32_bf16 v[0:3], v[140:143], v[136:139], v[0:3]
	s_branch .LBB0_855

.LBB0_947:
	s_or_b64 exec, exec, s[0:1]
	s_waitcnt vmcnt(1)
	v_mov_b32_e32 v1, v195
	s_cmpk_lt_i32 s2, 0x200
	s_waitcnt lgkmcnt(0)
	s_barrier
	s_nop 0
	s_nop 0
	s_nop 0
	s_nop 0
	s_nop 0
	s_nop 0
	s_cselect_b64 s[4:5], -1, 0
	s_cmpk_gt_i32 s2, 0x1ff
	v_readfirstlane_b32 s3, v1
	s_cbranch_scc1 .LBB0_950
	s_and_b32 s8, s2, 7
	s_bfe_u32 s1, s2, 0x50003
	s_cmpk_gt_i32 s2, 0xff
	s_cbranch_scc0 .LBB0_951
	s_lshl_b32 s0, s8, 1
	s_bfe_u32 s6, s2, 0x10003
	s_or_b32 s0, s0, s6
	s_lshr_b32 s73, s1, 3
	s_or_b32 s0, s0, 64
	s_bfe_u32 s38, s2, 0x20004
	s_cmp_gt_u32 s1, 15
	s_cselect_b32 s6, 0x2800000, 0
	s_lshl_b32 s12, s73, 10
	s_mov_b32 s11, 0
	s_and_b32 s7, s12, 0x400
	s_or_b32 s10, s6, s7
	s_mov_b32 s13, s11
	s_mov_b32 s74, 8
	s_cbranch_execz .LBB0_952
	s_branch .LBB0_953
